# scan SC_LOAD: running row pointers advanced per chunk instead of hipcc's 64-bit address arithmetic (22 -> 12 instructions per chunk)
# speedup vs baseline: 1.0122x; 1.0005x over previous
.LBB0_407:
	s_or_b64 exec, exec, s[12:13]
	v_add_f32_e32 v26, v32, v33
	v_sqrt_f32_e32 v26, v26
	s_waitcnt vmcnt(12)
	v_cvt_f32_f16_sdwa v27, v63 dst_sel:DWORD dst_unused:UNUSED_PAD src0_sel:WORD_1
	v_cvt_f32_f16_sdwa v21, v62 dst_sel:DWORD dst_unused:UNUSED_PAD src0_sel:WORD_1
	v_cvt_f32_f16_e32 v20, v62
	v_max_f32_e32 v26, 0x2b8cbccc, v26
	v_rcp_f32_e32 v26, v26
	v_cvt_f32_f16_e32 v28, v63
	v_cndmask_b32_e64 v29, v27, 1.0, s[0:1]
	s_lshl_b32 s92, s58, 5
	v_pk_mul_f32 v[30:31], v[16:17], v[26:27] op_sel_hi:[1,0]
	v_pk_mul_f32 v[26:27], v[18:19], v[26:27] op_sel_hi:[1,0]
	v_cndmask_b32_e64 v20, v20, 1.0, s[0:1]
	v_cndmask_b32_e64 v28, v28, 1.0, s[0:1]
	v_cndmask_b32_e64 v21, v21, 1.0, s[0:1]
	v_pk_mul_f32 v[14:15], v[14:15], v[30:31]
	v_pk_mul_f32 v[12:13], v[12:13], v[26:27]
	s_lshl_b32 s12, s90, 2
	v_pk_mul_f32 v[18:19], v[28:29], v[30:31] neg_lo:[0,1] neg_hi:[0,1]
	v_pk_mul_f32 v[16:17], v[20:21], v[26:27] neg_lo:[0,1] neg_hi:[0,1]
	v_pk_mul_f32 v[14:15], v[24:25], v[14:15]
	v_pk_mul_f32 v[12:13], v[22:23], v[12:13]
	v_lshl_add_u64 v[84:85], s[60:61], 0, v[42:43]
	v_lshl_add_u64 v[86:87], s[28:29], 0, v[42:43]
	v_lshl_add_u64 v[88:89], s[14:15], 0, v[42:43]
	s_add_u32 s58, s44, s12
	v_mov_b32_e32 v42, v43
	ds_write_b128 v41, v[16:19] offset:12288
	ds_write_b128 v41, v[12:15] offset:16384
	s_addc_u32 s59, s45, 0
	s_mov_b32 s93, 0
	s_mov_b64 s[62:63], 0
	s_mov_b64 s[64:65], -1
	v_mov_b64_e32 v[16:17], v[42:43]
	v_mov_b64_e32 v[18:19], v[42:43]
	v_mov_b64_e32 v[12:13], v[42:43]
	v_mov_b64_e32 v[14:15], v[42:43]
	v_mov_b32_e32 v233, 0
	v_and_b32_e32 v224, 15, v152
	v_mov_b32_e32 v216, 0
	v_mov_b32_e32 v225, 0x3c00
	v_cmp_eq_u32_e32 vcc, 0, v224
	v_mov_b32_e32 v226, 0x3c000000
	s_nop 1
	v_cndmask_b32_e32 v216, v216, v225, vcc
	v_cmp_eq_u32_e32 vcc, 1, v224
	s_nop 1
	v_cndmask_b32_e32 v216, v216, v226, vcc
	s_nop 0
	v_mov_b32_e32 v223, v216
	v_lshrrev_b32_e32 v224, 4, v152
	v_mul_u32_u24_e32 v224, 0x3f0, v224
	v_sub_u32_e32 v222, v105, v224
	v_lshlrev_b32_e32 v232, 1, v40
	v_mov_b32_e32 v229, s11
	v_mov_b32_e32 v227, s33
	v_add_u32_e32 v224, -16, v46
	v_cmp_gt_i32_e32 vcc, s87, v224
	v_add_u32_e32 v226, 0xffffbf80, v224
	v_ashrrev_i32_e32 v225, 31, v224
	v_cndmask_b32_e32 v224, v226, v224, vcc
	v_mov_b32_e32 v226, s10
	v_cndmask_b32_e32 v225, 0, v225, vcc
	v_cndmask_b32_e32 v227, v226, v227, vcc
	v_mov_b32_e32 v226, s3
	v_cndmask_b32_e32 v226, v226, v229, vcc
	v_lshlrev_b64 v[224:225], 11, v[224:225]
	v_lshl_add_u64 v[224:225], v[226:227], 0, v[224:225]
	s_lshl_b32 s42, s57, 1
	v_lshl_add_u64 v[224:225], v[224:225], 0, s[42:43]
	s_lshl_b32 s42, s92, 1
	v_lshl_add_u64 v[224:225], v[224:225], 0, s[42:43]
	v_lshl_add_u64 v[224:225], v[224:225], 0, v[232:233]
	s_movk_i32 s42, 0x1000
	v_lshl_add_u64 v[220:221], v[224:225], 0, s[42:43]
	v_add_u32_e32 v244, s91, v102
	v_add_u32_e32 v244, -16, v244
	v_mad_i64_i32 v[246:247], vcc, v244, s85, v[84:85]
	v_ashrrev_i32_e32 v245, 31, v244
	s_movk_i32 s42, 0x800
	v_lshl_add_u64 v[234:235], v[246:247], 0, s[42:43]
	v_lshlrev_b64 v[246:247], 11, v[244:245]
	v_lshl_add_u64 v[236:237], v[86:87], 0, v[246:247]
	v_lshl_add_u64 v[240:241], v[88:89], 0, v[246:247]
	v_sub_co_u32_e32 v244, vcc, v244, v38
	s_nop 1
	v_subbrev_co_u32_e32 v245, vcc, 0, v245, vcc
	v_lshlrev_b64 v[244:245], 11, v[244:245]
	v_lshl_add_u64 v[242:243], v[86:87], 0, v[244:245]
	s_waitcnt lgkmcnt(0)
	s_barrier
	s_branch .LBB0_410

.LBB0_410:
	s_lshl_b32 s94, s93, 4
	s_cmpk_lt_u32 s93, 0x7e
	s_cselect_b64 s[82:83], -1, 0
	s_cmpk_gt_u32 s93, 0x7d
	s_cselect_b64 s[66:67], -1, 0
	s_and_b64 vcc, exec, s[66:67]
	s_cbranch_vccnz .LBB0_412
	s_mov_b64 s[50:51], 0x18000
	v_lshl_add_u64 v[234:235], v[234:235], 0, s[50:51]
	s_mov_b32 s50, 0x8000
	v_lshl_add_u64 v[236:237], v[236:237], 0, s[50:51]
	v_lshl_add_u64 v[240:241], v[240:241], 0, s[50:51]
	v_lshl_add_u64 v[242:243], v[242:243], 0, s[50:51]
	global_load_dwordx2 v[48:49], v[234:235], off offset:-2048
	global_load_dwordx2 v[50:51], v[234:235], off
	global_load_dwordx2 v[52:53], v[234:235], off offset:2048
	global_load_dwordx2 v[54:55], v[236:237], off
	global_load_dwordx2 v[56:57], v[240:241], off
	global_load_dwordx2 v[62:63], v[242:243], off

.LBB0_421:
	s_or_b64 exec, exec, s[12:13]
	v_add_f32_e32 v35, v42, v116
	v_sqrt_f32_e32 v35, v35
	v_cvt_f32_f16_sdwa v33, v74 dst_sel:DWORD dst_unused:UNUSED_PAD src0_sel:WORD_1
	v_cvt_f32_f16_e32 v34, v74
	v_cvt_f32_f16_sdwa v95, v75 dst_sel:DWORD dst_unused:UNUSED_PAD src0_sel:WORD_1
	v_max_f32_e32 v35, 0x2b8cbccc, v35
	v_rcp_f32_e32 v42, v35
	v_cvt_f32_f16_e32 v94, v75
	v_cndmask_b32_e64 v34, v34, 1.0, s[0:1]
	v_cndmask_b32_e64 v35, v33, 1.0, s[0:1]
	v_pk_mul_f32 v[96:97], v[28:29], v[42:43] op_sel_hi:[1,0]
	v_pk_mul_f32 v[116:117], v[30:31], v[42:43] op_sel_hi:[1,0]
	v_cndmask_b32_e64 v94, v94, 1.0, s[0:1]
	v_cndmask_b32_e64 v95, v95, 1.0, s[0:1]
	v_pk_mul_f32 v[26:27], v[26:27], v[96:97]
	v_pk_mul_f32 v[24:25], v[24:25], v[116:117]
	s_lshl_b32 s95, s96, 4
	v_pk_mul_f32 v[30:31], v[94:95], v[96:97] neg_lo:[0,1] neg_hi:[0,1]
	v_pk_mul_f32 v[28:29], v[34:35], v[116:117] neg_lo:[0,1] neg_hi:[0,1]
	v_pk_mul_f32 v[26:27], v[92:93], v[26:27]
	v_pk_mul_f32 v[24:25], v[90:91], v[24:25]
	s_cmpk_gt_u32 s93, 0x7c
	ds_write_b128 v32, v[28:31] offset:12288
	ds_write_b128 v32, v[24:27] offset:16384
	s_waitcnt lgkmcnt(0)
	s_barrier
	s_cbranch_scc1 .LBB0_423
	s_mov_b64 s[50:51], 0x18000
	v_lshl_add_u64 v[234:235], v[234:235], 0, s[50:51]
	s_mov_b32 s50, 0x8000
	v_lshl_add_u64 v[236:237], v[236:237], 0, s[50:51]
	v_lshl_add_u64 v[240:241], v[240:241], 0, s[50:51]
	v_lshl_add_u64 v[242:243], v[242:243], 0, s[50:51]
	global_load_dwordx2 v[58:59], v[234:235], off offset:-2048
	global_load_dwordx2 v[60:61], v[234:235], off
	global_load_dwordx2 v[64:65], v[234:235], off offset:2048
	global_load_dwordx2 v[66:67], v[236:237], off
	global_load_dwordx2 v[68:69], v[240:241], off
	global_load_dwordx2 v[74:75], v[242:243], off

.LBB0_432:
	s_or_b64 exec, exec, s[12:13]
	v_add_f32_e32 v27, v42, v116
	v_sqrt_f32_e32 v27, v27
	s_waitcnt vmcnt(0)
	v_cvt_f32_f16_sdwa v25, v82 dst_sel:DWORD dst_unused:UNUSED_PAD src0_sel:WORD_1
	v_cvt_f32_f16_e32 v26, v82
	v_cvt_f32_f16_sdwa v95, v83 dst_sel:DWORD dst_unused:UNUSED_PAD src0_sel:WORD_1
	v_max_f32_e32 v27, 0x2b8cbccc, v27
	v_rcp_f32_e32 v42, v27
	v_cvt_f32_f16_e32 v94, v83
	v_cndmask_b32_e64 v26, v26, 1.0, s[0:1]
	v_cndmask_b32_e64 v27, v25, 1.0, s[0:1]
	v_pk_mul_f32 v[96:97], v[20:21], v[42:43] op_sel_hi:[1,0]
	v_pk_mul_f32 v[116:117], v[22:23], v[42:43] op_sel_hi:[1,0]
	v_cndmask_b32_e64 v94, v94, 1.0, s[0:1]
	v_cndmask_b32_e64 v95, v95, 1.0, s[0:1]
	v_pk_mul_f32 v[18:19], v[18:19], v[96:97]
	v_pk_mul_f32 v[16:17], v[16:17], v[116:117]
	v_pk_mul_f32 v[22:23], v[94:95], v[96:97] neg_lo:[0,1] neg_hi:[0,1]
	v_pk_mul_f32 v[20:21], v[26:27], v[116:117] neg_lo:[0,1] neg_hi:[0,1]
	v_pk_mul_f32 v[18:19], v[92:93], v[18:19]
	v_pk_mul_f32 v[16:17], v[30:31], v[16:17]
	s_cmpk_gt_u32 s93, 0x7b
	ds_write_b128 v24, v[20:23] offset:12288
	ds_write_b128 v24, v[16:19] offset:16384
	s_waitcnt lgkmcnt(0)
	s_barrier
	s_cbranch_scc1 .LBB0_434
	s_mov_b64 s[50:51], 0x18000
	v_lshl_add_u64 v[234:235], v[234:235], 0, s[50:51]
	s_mov_b32 s50, 0x8000
	v_lshl_add_u64 v[236:237], v[236:237], 0, s[50:51]
	v_lshl_add_u64 v[240:241], v[240:241], 0, s[50:51]
	v_lshl_add_u64 v[242:243], v[242:243], 0, s[50:51]
	global_load_dwordx2 v[70:71], v[234:235], off offset:-2048
	global_load_dwordx2 v[72:73], v[234:235], off
	global_load_dwordx2 v[76:77], v[234:235], off offset:2048
	global_load_dwordx2 v[78:79], v[236:237], off
	global_load_dwordx2 v[80:81], v[240:241], off
	global_load_dwordx2 v[82:83], v[242:243], off
